# scale epilogue (in-proj, q, lora GEMMs): the 8 row-scale loads issued together behind one wait; null-pointer case branches around them once
# speedup vs baseline: 1.0184x; 1.0052x over previous
.LBB0_653:
	s_and_b64 vcc, exec, s[6:7]
	s_cbranch_vccz .LBB0_674
	s_cmp_gt_i32 s47, 0
	s_mov_b64 s[6:7], -1
	s_cbranch_scc0 .LBB0_672
	s_lshl_b32 s1, s15, 8
	v_add_u32_e32 v134, s1, v170
	v_ashrrev_i32_e32 v135, 31, v134
	v_mov_b32_e32 v132, 0x358637bd
	v_mov_b32_e32 v142, 0x358637bd
	v_mov_b32_e32 v143, 0x358637bd
	v_mov_b32_e32 v141, 0x358637bd
	v_mov_b32_e32 v139, 0x358637bd
	v_mov_b32_e32 v140, 0x358637bd
	v_mov_b32_e32 v131, 0x358637bd
	v_mov_b32_e32 v137, 0x358637bd
	v_add_u32_e32 v138, 0x80, v134
	v_add_u32_e32 v136, 0x90, v134
	v_add_u32_e32 v130, 0xa0, v134
	v_add_u32_e32 v128, 0xb0, v134
	v_ashrrev_i32_e32 v129, 31, v128
	s_andn2_b64 vcc, exec, s[64:65]
	s_waitcnt lgkmcnt(0)
	s_cbranch_vccnz .LBB0_671
	v_lshl_add_u64 v[222:223], v[134:135], 3, s[96:97]
	global_load_dwordx2 v[222:223], v[222:223], off
	v_add_u32_e32 v224, 16, v134
	v_ashrrev_i32_e32 v225, 31, v224
	v_lshl_add_u64 v[224:225], v[224:225], 3, s[96:97]
	global_load_dwordx2 v[224:225], v[224:225], off
	v_add_u32_e32 v226, 32, v134
	v_ashrrev_i32_e32 v227, 31, v226
	v_lshl_add_u64 v[226:227], v[226:227], 3, s[96:97]
	global_load_dwordx2 v[226:227], v[226:227], off
	v_add_u32_e32 v228, 48, v134
	v_ashrrev_i32_e32 v229, 31, v228
	v_lshl_add_u64 v[228:229], v[228:229], 3, s[96:97]
	global_load_dwordx2 v[228:229], v[228:229], off
	v_add_u32_e32 v230, 0x80, v134
	v_ashrrev_i32_e32 v231, 31, v230
	v_lshl_add_u64 v[230:231], v[230:231], 3, s[96:97]
	global_load_dwordx2 v[230:231], v[230:231], off
	v_add_u32_e32 v232, 0x90, v134
	v_ashrrev_i32_e32 v233, 31, v232
	v_lshl_add_u64 v[232:233], v[232:233], 3, s[96:97]
	global_load_dwordx2 v[232:233], v[232:233], off
	v_add_u32_e32 v234, 0xa0, v134
	v_ashrrev_i32_e32 v235, 31, v234
	v_lshl_add_u64 v[234:235], v[234:235], 3, s[96:97]
	global_load_dwordx2 v[234:235], v[234:235], off
	v_lshl_add_u64 v[236:237], v[128:129], 3, s[96:97]
	global_load_dwordx2 v[236:237], v[236:237], off
	s_flbit_i32_b32 s1, 0
	s_min_u32 s2, s1, 32
	s_sub_i32 s1, 32, s2
	s_waitcnt vmcnt(0)
	v_mov_b32_e32 v156, v223
	v_lshlrev_b64 v[144:145], s2, v[156:157]
	v_min_u32_e32 v146, 1, v144
	v_or_b32_e32 v146, v145, v146
	v_cvt_f32_u32_e32 v146, v146
	v_cvt_f32_u32_e32 v147, v222
	v_ldexp_f32 v146, v146, s1
	v_mul_f32_e32 v146, 0x43800000, v146
	v_fmac_f32_e32 v146, 0x33800000, v147
	v_fmamk_f32 v132, v146, 0x3a800000, v194
	v_mov_b32_e32 v156, v225
	v_lshlrev_b64 v[144:145], s2, v[156:157]
	v_min_u32_e32 v146, 1, v144
	v_or_b32_e32 v146, v145, v146
	v_cvt_f32_u32_e32 v146, v146
	v_cvt_f32_u32_e32 v147, v224
	v_ldexp_f32 v146, v146, s1
	v_mul_f32_e32 v146, 0x43800000, v146
	v_fmac_f32_e32 v146, 0x33800000, v147
	v_fmamk_f32 v142, v146, 0x3a800000, v194
	v_mov_b32_e32 v156, v227
	v_lshlrev_b64 v[144:145], s2, v[156:157]
	v_min_u32_e32 v146, 1, v144
	v_or_b32_e32 v146, v145, v146
	v_cvt_f32_u32_e32 v146, v146
	v_cvt_f32_u32_e32 v147, v226
	v_ldexp_f32 v146, v146, s1
	v_mul_f32_e32 v146, 0x43800000, v146
	v_fmac_f32_e32 v146, 0x33800000, v147
	v_fmamk_f32 v143, v146, 0x3a800000, v194
	v_mov_b32_e32 v156, v229
	v_lshlrev_b64 v[144:145], s2, v[156:157]
	v_min_u32_e32 v146, 1, v144
	v_or_b32_e32 v146, v145, v146
	v_cvt_f32_u32_e32 v146, v146
	v_cvt_f32_u32_e32 v147, v228
	v_ldexp_f32 v146, v146, s1
	v_mul_f32_e32 v146, 0x43800000, v146
	v_fmac_f32_e32 v146, 0x33800000, v147
	v_fmamk_f32 v141, v146, 0x3a800000, v194
	v_mov_b32_e32 v156, v231
	v_lshlrev_b64 v[144:145], s2, v[156:157]
	v_min_u32_e32 v146, 1, v144
	v_or_b32_e32 v146, v145, v146
	v_cvt_f32_u32_e32 v146, v146
	v_cvt_f32_u32_e32 v147, v230
	v_ldexp_f32 v146, v146, s1
	v_mul_f32_e32 v146, 0x43800000, v146
	v_fmac_f32_e32 v146, 0x33800000, v147
	v_fmamk_f32 v139, v146, 0x3a800000, v194
	v_mov_b32_e32 v156, v233
	v_lshlrev_b64 v[144:145], s2, v[156:157]
	v_min_u32_e32 v146, 1, v144
	v_or_b32_e32 v146, v145, v146
	v_cvt_f32_u32_e32 v146, v146
	v_cvt_f32_u32_e32 v147, v232
	v_ldexp_f32 v146, v146, s1
	v_mul_f32_e32 v146, 0x43800000, v146
	v_fmac_f32_e32 v146, 0x33800000, v147
	v_fmamk_f32 v140, v146, 0x3a800000, v194
	v_mov_b32_e32 v156, v235
	v_lshlrev_b64 v[144:145], s2, v[156:157]
	v_min_u32_e32 v146, 1, v144
	v_or_b32_e32 v146, v145, v146
	v_cvt_f32_u32_e32 v146, v146
	v_cvt_f32_u32_e32 v147, v234
	v_ldexp_f32 v146, v146, s1
	v_mul_f32_e32 v146, 0x43800000, v146
	v_fmac_f32_e32 v146, 0x33800000, v147
	v_fmamk_f32 v131, v146, 0x3a800000, v194
	v_mov_b32_e32 v156, v237
	v_lshlrev_b64 v[144:145], s2, v[156:157]
	v_min_u32_e32 v146, 1, v144
	v_or_b32_e32 v146, v145, v146
	v_cvt_f32_u32_e32 v146, v146
	v_cvt_f32_u32_e32 v147, v236
	v_ldexp_f32 v146, v146, s1
	v_mul_f32_e32 v146, 0x43800000, v146
	v_fmac_f32_e32 v146, 0x33800000, v147
	v_fmamk_f32 v137, v146, 0x3a800000, v194
